# prologue XB (bf16 x) row stores write-back instead of sc1 (row loop waits no longer include write-through acks)
# speedup vs baseline: 1.0129x; 1.0050x over previous
; __device__ __forceinline__ unsigned pk2(float lo, float hi) { return f2bf(lo) | (f2bf(hi) << 16); }
; __global__ void __launch_bounds__(NTHREADS, 2) mega_fwd(Args args) {
;     ...
;         for (int row = gw; row < S; row += ngw) {
;             const f32x4* xr = (const f32x4*)(x_in + (size_t)row * D) + 2 * lane; float s = 0.f;
;             bf16* orow = XB + (size_t)row * D + 8 * lane;
; #pragma unroll
;             for (int j = 0; j < 4; ++j) { const f32x4 v = xr[128 * j], w = xr[128 * j + 1];
;                 s += ((v[0] * v[0] + v[1] * v[1]) + (v[2] * v[2] + v[3] * v[3])) + ((w[0] * w[0] + w[1] * w[1]) + (w[2] * w[2] + w[3] * w[3]));
;                 u32x4 o; o.x = pk2(v[0], v[1]); o.y = pk2(v[2], v[3]); o.z = pk2(w[0], w[1]); o.w = pk2(w[2], w[3]);
;                 asm volatile("global_store_dwordx4 %0, %1, off sc1\n\ts_nop 1" :: "v"(orow + 512 * j), "v"(o) : "memory"); }
.LBB0_24:
	v_add_co_u32_e32 v36, vcc, 0xfffff000, v10
	s_waitcnt lgkmcnt(0)
	v_lshl_add_u64 v[12:13], v[10:11], 0, s[22:23]
	v_addc_co_u32_e32 v37, vcc, -1, v11, vcc
	global_load_dwordx4 v[20:23], v[36:37], off offset:-2064
	global_load_dwordx4 v[24:27], v[12:13], off offset:16
	v_lshl_add_u64 v[12:13], s[12:13], 0, v[8:9]
	v_lshl_add_u64 v[32:33], v[12:13], 0, s[24:25]
	v_lshl_add_u64 v[40:41], v[12:13], 0, s[26:27]
	v_lshl_add_u64 v[48:49], v[12:13], 0, s[28:29]
	s_waitcnt vmcnt(0)
	v_and_b32_sdwa v29, v23, v3 dst_sel:DWORD dst_unused:UNUSED_PAD src0_sel:WORD_1 src1_sel:DWORD
	v_and_b32_sdwa v30, v21, v3 dst_sel:DWORD dst_unused:UNUSED_PAD src0_sel:WORD_1 src1_sel:DWORD
	v_and_b32_sdwa v35, v27, v3 dst_sel:DWORD dst_unused:UNUSED_PAD src0_sel:WORD_1 src1_sel:DWORD
	v_and_b32_sdwa v38, v25, v3 dst_sel:DWORD dst_unused:UNUSED_PAD src0_sel:WORD_1 src1_sel:DWORD
	v_and_b32_sdwa v19, v22, v3 dst_sel:DWORD dst_unused:UNUSED_PAD src0_sel:WORD_1 src1_sel:DWORD
	v_and_b32_sdwa v28, v20, v3 dst_sel:DWORD dst_unused:UNUSED_PAD src0_sel:WORD_1 src1_sel:DWORD
	v_and_b32_sdwa v31, v26, v3 dst_sel:DWORD dst_unused:UNUSED_PAD src0_sel:WORD_1 src1_sel:DWORD
	v_and_b32_sdwa v34, v24, v3 dst_sel:DWORD dst_unused:UNUSED_PAD src0_sel:WORD_1 src1_sel:DWORD
	v_add3_u32 v29, v23, v29, s9
	v_add3_u32 v30, v21, v30, s9
	v_add3_u32 v35, v27, v35, s9
	v_add3_u32 v38, v25, v38, s9
	v_add3_u32 v28, v20, v28, s9
	v_add3_u32 v19, v22, v19, s9
	v_add3_u32 v34, v24, v34, s9
	v_add3_u32 v31, v26, v31, s9
	v_and_b32_e32 v29, 0xffff0000, v29
	v_and_b32_e32 v30, 0xffff0000, v30
	v_and_b32_e32 v35, 0xffff0000, v35
	v_and_b32_e32 v38, 0xffff0000, v38
	v_or_b32_sdwa v29, v29, v19 dst_sel:DWORD dst_unused:UNUSED_PAD src0_sel:DWORD src1_sel:WORD_1
	v_or_b32_sdwa v28, v30, v28 dst_sel:DWORD dst_unused:UNUSED_PAD src0_sel:DWORD src1_sel:WORD_1
	v_or_b32_sdwa v31, v35, v31 dst_sel:DWORD dst_unused:UNUSED_PAD src0_sel:DWORD src1_sel:WORD_1
	v_or_b32_sdwa v30, v38, v34 dst_sel:DWORD dst_unused:UNUSED_PAD src0_sel:DWORD src1_sel:WORD_1
	global_store_dwordx4 v[32:33], v[28:31], off
	s_nop 1
	global_load_dwordx4 v[28:31], v[36:37], off offset:-16
	global_load_dwordx4 v[32:35], v[10:11], off offset:-4096
	s_waitcnt vmcnt(1)
	v_and_b32_sdwa v37, v31, v3 dst_sel:DWORD dst_unused:UNUSED_PAD src0_sel:WORD_1 src1_sel:DWORD
	v_and_b32_sdwa v38, v29, v3 dst_sel:DWORD dst_unused:UNUSED_PAD src0_sel:WORD_1 src1_sel:DWORD
	s_waitcnt vmcnt(0)
	v_and_b32_sdwa v43, v35, v3 dst_sel:DWORD dst_unused:UNUSED_PAD src0_sel:WORD_1 src1_sel:DWORD
	v_and_b32_sdwa v44, v33, v3 dst_sel:DWORD dst_unused:UNUSED_PAD src0_sel:WORD_1 src1_sel:DWORD
	v_and_b32_sdwa v19, v30, v3 dst_sel:DWORD dst_unused:UNUSED_PAD src0_sel:WORD_1 src1_sel:DWORD
	v_and_b32_sdwa v36, v28, v3 dst_sel:DWORD dst_unused:UNUSED_PAD src0_sel:WORD_1 src1_sel:DWORD
	v_and_b32_sdwa v39, v34, v3 dst_sel:DWORD dst_unused:UNUSED_PAD src0_sel:WORD_1 src1_sel:DWORD
	v_and_b32_sdwa v42, v32, v3 dst_sel:DWORD dst_unused:UNUSED_PAD src0_sel:WORD_1 src1_sel:DWORD
	v_add3_u32 v37, v31, v37, s9
	v_add3_u32 v38, v29, v38, s9
	v_add3_u32 v43, v35, v43, s9
	v_add3_u32 v44, v33, v44, s9
	v_add3_u32 v36, v28, v36, s9
	v_add3_u32 v19, v30, v19, s9
	v_add3_u32 v42, v32, v42, s9
	v_add3_u32 v39, v34, v39, s9
	v_and_b32_e32 v37, 0xffff0000, v37
	v_and_b32_e32 v38, 0xffff0000, v38
	v_and_b32_e32 v43, 0xffff0000, v43
	v_and_b32_e32 v44, 0xffff0000, v44
	v_or_b32_sdwa v37, v37, v19 dst_sel:DWORD dst_unused:UNUSED_PAD src0_sel:DWORD src1_sel:WORD_1
	v_or_b32_sdwa v36, v38, v36 dst_sel:DWORD dst_unused:UNUSED_PAD src0_sel:DWORD src1_sel:WORD_1
	v_or_b32_sdwa v39, v43, v39 dst_sel:DWORD dst_unused:UNUSED_PAD src0_sel:DWORD src1_sel:WORD_1
	v_or_b32_sdwa v38, v44, v42 dst_sel:DWORD dst_unused:UNUSED_PAD src0_sel:DWORD src1_sel:WORD_1
	global_store_dwordx4 v[40:41], v[36:39], off
	s_nop 1
	global_load_dwordx4 v[36:39], v[10:11], off offset:-2064
	global_load_dwordx4 v[40:43], v[10:11], off offset:-2048
	s_waitcnt vmcnt(1)
	v_and_b32_sdwa v45, v39, v3 dst_sel:DWORD dst_unused:UNUSED_PAD src0_sel:WORD_1 src1_sel:DWORD
	v_and_b32_sdwa v46, v37, v3 dst_sel:DWORD dst_unused:UNUSED_PAD src0_sel:WORD_1 src1_sel:DWORD
	s_waitcnt vmcnt(0)
; __device__ __forceinline__ unsigned pk2(float lo, float hi) { return f2bf(lo) | (f2bf(hi) << 16); }
; __global__ void __launch_bounds__(NTHREADS, 2) mega_fwd(Args args) {
;     ...
;             const f32x4* xr = (const f32x4*)(x_in + (size_t)row * D) + 2 * lane; float s = 0.f;
;             bf16* orow = XB + (size_t)row * D + 8 * lane;
; #pragma unroll
;             for (int j = 0; j < 4; ++j) { const f32x4 v = xr[128 * j], w = xr[128 * j + 1];
;                 s += ((v[0] * v[0] + v[1] * v[1]) + (v[2] * v[2] + v[3] * v[3])) + ((w[0] * w[0] + w[1] * w[1]) + (w[2] * w[2] + w[3] * w[3]));
;                 u32x4 o; o.x = pk2(v[0], v[1]); o.y = pk2(v[2], v[3]); o.z = pk2(w[0], w[1]); o.w = pk2(w[2], w[3]);
;                 asm volatile("global_store_dwordx4 %0, %1, off sc1\n\ts_nop 1" :: "v"(orow + 512 * j), "v"(o) : "memory"); }
;             s = wave_sum(s); if (lane < 8) ssq_x[(size_t)row * 8 + lane] = (lane == 0) ? s : 0.f;
	v_and_b32_sdwa v51, v43, v3 dst_sel:DWORD dst_unused:UNUSED_PAD src0_sel:WORD_1 src1_sel:DWORD
	v_and_b32_sdwa v52, v41, v3 dst_sel:DWORD dst_unused:UNUSED_PAD src0_sel:WORD_1 src1_sel:DWORD
	v_and_b32_sdwa v19, v38, v3 dst_sel:DWORD dst_unused:UNUSED_PAD src0_sel:WORD_1 src1_sel:DWORD
	v_and_b32_sdwa v44, v36, v3 dst_sel:DWORD dst_unused:UNUSED_PAD src0_sel:WORD_1 src1_sel:DWORD
	v_and_b32_sdwa v47, v42, v3 dst_sel:DWORD dst_unused:UNUSED_PAD src0_sel:WORD_1 src1_sel:DWORD
	v_and_b32_sdwa v50, v40, v3 dst_sel:DWORD dst_unused:UNUSED_PAD src0_sel:WORD_1 src1_sel:DWORD
	v_add3_u32 v45, v39, v45, s9
	v_add3_u32 v46, v37, v46, s9
	v_add3_u32 v51, v43, v51, s9
	v_add3_u32 v52, v41, v52, s9
	v_add3_u32 v44, v36, v44, s9
	v_add3_u32 v19, v38, v19, s9
	v_add3_u32 v50, v40, v50, s9
	v_add3_u32 v47, v42, v47, s9
	v_and_b32_e32 v45, 0xffff0000, v45
	v_and_b32_e32 v46, 0xffff0000, v46
	v_and_b32_e32 v51, 0xffff0000, v51
	v_and_b32_e32 v52, 0xffff0000, v52
	v_or_b32_sdwa v45, v45, v19 dst_sel:DWORD dst_unused:UNUSED_PAD src0_sel:DWORD src1_sel:WORD_1
	v_or_b32_sdwa v44, v46, v44 dst_sel:DWORD dst_unused:UNUSED_PAD src0_sel:DWORD src1_sel:WORD_1
	v_or_b32_sdwa v47, v51, v47 dst_sel:DWORD dst_unused:UNUSED_PAD src0_sel:DWORD src1_sel:WORD_1
	v_or_b32_sdwa v46, v52, v50 dst_sel:DWORD dst_unused:UNUSED_PAD src0_sel:DWORD src1_sel:WORD_1
	global_store_dwordx4 v[48:49], v[44:47], off
	s_nop 1
	global_load_dwordx4 v[44:47], v[10:11], off offset:-16
	global_load_dwordx4 v[48:51], v[10:11], off
	v_mul_f32_e32 v19, v21, v21
	v_mul_f32_e32 v21, v23, v23
	v_mul_f32_e32 v23, v25, v25
	v_mul_f32_e32 v25, v27, v27
	v_fmac_f32_e32 v19, v20, v20
	v_fmac_f32_e32 v21, v22, v22
	v_fmac_f32_e32 v23, v24, v24
	v_fmac_f32_e32 v25, v26, v26
	v_add_f32_e32 v19, v19, v21
	v_add_f32_e32 v20, v23, v25
	v_add_f32_e32 v19, v19, v20
	v_mul_f32_e32 v20, v29, v29
	v_mul_f32_e32 v21, v31, v31
	v_mul_f32_e32 v22, v33, v33
	v_mul_f32_e32 v23, v35, v35
	v_fmac_f32_e32 v20, v28, v28
	v_fmac_f32_e32 v21, v30, v30
	v_fmac_f32_e32 v22, v32, v32
	v_fmac_f32_e32 v23, v34, v34
	v_add_f32_e32 v20, v20, v21
	v_add_f32_e32 v21, v22, v23
	v_add_f32_e32 v20, v20, v21
	v_add_f32_e32 v19, v19, v20
	v_mul_f32_e32 v20, v37, v37
	v_mul_f32_e32 v21, v39, v39
	v_mul_f32_e32 v22, v41, v41
	v_mul_f32_e32 v23, v43, v43
	v_fmac_f32_e32 v20, v36, v36
	v_fmac_f32_e32 v21, v38, v38
	v_fmac_f32_e32 v22, v40, v40
	v_fmac_f32_e32 v23, v42, v42
	v_add_f32_e32 v20, v20, v21
	v_add_f32_e32 v21, v22, v23
	v_add_f32_e32 v20, v20, v21
	v_add_f32_e32 v19, v19, v20
	s_waitcnt vmcnt(1)
	v_mul_f32_e32 v20, v45, v45
	v_mul_f32_e32 v21, v47, v47
	s_waitcnt vmcnt(0)
	v_mul_f32_e32 v22, v49, v49
	v_mul_f32_e32 v23, v51, v51
	v_fmac_f32_e32 v20, v44, v44
	v_fmac_f32_e32 v21, v46, v46
	v_fmac_f32_e32 v22, v48, v48
	v_fmac_f32_e32 v23, v50, v50
	v_add_f32_e32 v20, v20, v21
	v_add_f32_e32 v21, v22, v23
	v_add_f32_e32 v20, v20, v21
	v_add_f32_e32 v19, v19, v20
	ds_bpermute_b32 v21, v5, v19
	v_and_b32_sdwa v20, v47, v3 dst_sel:DWORD dst_unused:UNUSED_PAD src0_sel:WORD_1 src1_sel:DWORD
	v_and_b32_sdwa v22, v45, v3 dst_sel:DWORD dst_unused:UNUSED_PAD src0_sel:WORD_1 src1_sel:DWORD
	v_and_b32_sdwa v24, v46, v3 dst_sel:DWORD dst_unused:UNUSED_PAD src0_sel:WORD_1 src1_sel:DWORD
	v_and_b32_sdwa v25, v44, v3 dst_sel:DWORD dst_unused:UNUSED_PAD src0_sel:WORD_1 src1_sel:DWORD
	s_waitcnt lgkmcnt(0)
	v_add_f32_e32 v19, v19, v21
	ds_bpermute_b32 v23, v14, v19
	v_add3_u32 v20, v47, v20, s9
	v_add3_u32 v22, v45, v22, s9
	v_add3_u32 v25, v44, v25, s9
	v_add3_u32 v24, v46, v24, s9
	s_waitcnt lgkmcnt(0)
	v_add_f32_e32 v19, v19, v23
	ds_bpermute_b32 v23, v15, v19
	v_and_b32_e32 v20, 0xffff0000, v20
	v_and_b32_e32 v22, 0xffff0000, v22
	v_or_b32_sdwa v21, v20, v24 dst_sel:DWORD dst_unused:UNUSED_PAD src0_sel:DWORD src1_sel:WORD_1
	v_or_b32_sdwa v20, v22, v25 dst_sel:DWORD dst_unused:UNUSED_PAD src0_sel:DWORD src1_sel:WORD_1
	s_waitcnt lgkmcnt(0)
	v_add_f32_e32 v19, v19, v23
	ds_bpermute_b32 v23, v16, v19
	v_and_b32_sdwa v25, v51, v3 dst_sel:DWORD dst_unused:UNUSED_PAD src0_sel:WORD_1 src1_sel:DWORD
	v_and_b32_sdwa v26, v49, v3 dst_sel:DWORD dst_unused:UNUSED_PAD src0_sel:WORD_1 src1_sel:DWORD
	v_and_b32_sdwa v22, v50, v3 dst_sel:DWORD dst_unused:UNUSED_PAD src0_sel:WORD_1 src1_sel:DWORD
	v_and_b32_sdwa v24, v48, v3 dst_sel:DWORD dst_unused:UNUSED_PAD src0_sel:WORD_1 src1_sel:DWORD
	s_waitcnt lgkmcnt(0)
	v_add_f32_e32 v19, v19, v23
	ds_bpermute_b32 v27, v17, v19
	v_add3_u32 v25, v51, v25, s9
	v_add3_u32 v26, v49, v26, s9
	v_add3_u32 v24, v48, v24, s9
	v_add3_u32 v22, v50, v22, s9
	v_and_b32_e32 v25, 0xffff0000, v25
	v_and_b32_e32 v26, 0xffff0000, v26
	v_or_b32_sdwa v23, v25, v22 dst_sel:DWORD dst_unused:UNUSED_PAD src0_sel:DWORD src1_sel:WORD_1
	v_or_b32_sdwa v22, v26, v24 dst_sel:DWORD dst_unused:UNUSED_PAD src0_sel:DWORD src1_sel:WORD_1
	v_lshl_add_u64 v[24:25], v[12:13], 0, s[30:31]
	s_waitcnt lgkmcnt(0)
	v_add_f32_e32 v12, v19, v27
	ds_bpermute_b32 v13, v18, v12
	global_store_dwordx4 v[24:25], v[20:23], off
	s_nop 1
	s_and_saveexec_b64 s[34:35], s[6:7]
	s_cbranch_execz .LBB0_23
	s_waitcnt lgkmcnt(0)
	v_add_f32_e32 v12, v12, v13
	v_lshl_add_u64 v[20:21], s[12:13], 0, v[6:7]
	v_cndmask_b32_e64 v12, 0, v12, s[4:5]
	flat_store_dword v[20:21], v12
	s_branch .LBB0_23
